# RG-LRU finalize carry scan: 8 chunk steps per trip (32 loads in flight) plus a 2-step remainder trip: longest carry needs 10 round trips instead of 18
# baseline (speedup 1.0000x reference)
; __device__ void lru_final_item(const Params& P, int l, int item) {
;     ...
;   for (int jj = 0; jj < j; ++jj) {
;     const float* ap = P.AP + (size_t)(b * 64 + jj) * 512 + lane * 8;
;     const float* he = P.HE + (size_t)(b * 64 + jj) * 512 + lane * 8;
;     const float4 a0 = *(const float4*)ap, a1 = *(const float4*)(ap + 4);
;     const float4 h0 = *(const float4*)he, h1 = *(const float4*)(he + 4);
;     carry[0] = a0.x * carry[0] + h0.x; carry[1] = a0.y * carry[1] + h0.y; carry[2] = a0.z * carry[2] + h0.z; carry[3] = a0.w * carry[3] + h0.w;
;     carry[4] = a1.x * carry[4] + h1.x; carry[5] = a1.y * carry[5] + h1.y; carry[6] = a1.z * carry[6] + h1.z; carry[7] = a1.w * carry[7] + h1.w;
;   }
.Llf_chunk8:
	s_sub_u32 s38, s4, s0
	s_cmp_lt_u32 s38, 0x4000
	s_cbranch_scc1 .Llf_chunk
	v_lshl_add_u64 v[56:57], v[2:3], 0, s[0:1]
	v_lshl_add_u64 v[58:59], v[0:1], 0, s[0:1]
	global_load_dwordx4 v[60:63], v[58:59], off offset:16
	global_load_dwordx4 v[64:67], v[56:57], off offset:16
	global_load_dwordx4 v[68:71], v[56:57], off
	global_load_dwordx4 v[72:75], v[58:59], off
	s_add_u32 s0, s0, 0x800
	s_addc_u32 s1, s1, 0
	v_lshl_add_u64 v[56:57], v[2:3], 0, s[0:1]
	v_lshl_add_u64 v[58:59], v[0:1], 0, s[0:1]
	global_load_dwordx4 v[76:79], v[58:59], off offset:16
	global_load_dwordx4 v[80:83], v[56:57], off offset:16
	global_load_dwordx4 v[84:87], v[56:57], off
	global_load_dwordx4 v[88:91], v[58:59], off
	s_add_u32 s0, s0, 0x800
	s_addc_u32 s1, s1, 0
	v_lshl_add_u64 v[56:57], v[2:3], 0, s[0:1]
	v_lshl_add_u64 v[58:59], v[0:1], 0, s[0:1]
	global_load_dwordx4 v[92:95], v[58:59], off offset:16
	global_load_dwordx4 v[96:99], v[56:57], off offset:16
	global_load_dwordx4 v[100:103], v[56:57], off
	global_load_dwordx4 v[104:107], v[58:59], off
	s_add_u32 s0, s0, 0x800
	s_addc_u32 s1, s1, 0
	v_lshl_add_u64 v[56:57], v[2:3], 0, s[0:1]
	v_lshl_add_u64 v[58:59], v[0:1], 0, s[0:1]
	global_load_dwordx4 v[108:111], v[58:59], off offset:16
	global_load_dwordx4 v[112:115], v[56:57], off offset:16
	global_load_dwordx4 v[116:119], v[56:57], off
	global_load_dwordx4 v[120:123], v[58:59], off
	s_add_u32 s0, s0, 0x800
	s_addc_u32 s1, s1, 0
	v_lshl_add_u64 v[56:57], v[2:3], 0, s[0:1]
	v_lshl_add_u64 v[58:59], v[0:1], 0, s[0:1]
	global_load_dwordx4 v[124:127], v[58:59], off offset:16
	global_load_dwordx4 v[128:131], v[56:57], off offset:16
	global_load_dwordx4 v[132:135], v[56:57], off
	global_load_dwordx4 v[136:139], v[58:59], off
	s_add_u32 s0, s0, 0x800
	s_addc_u32 s1, s1, 0
	v_lshl_add_u64 v[56:57], v[2:3], 0, s[0:1]
	v_lshl_add_u64 v[58:59], v[0:1], 0, s[0:1]
	global_load_dwordx4 v[140:143], v[58:59], off offset:16
	global_load_dwordx4 v[144:147], v[56:57], off offset:16
	global_load_dwordx4 v[148:151], v[56:57], off
	global_load_dwordx4 v[152:155], v[58:59], off
	s_add_u32 s0, s0, 0x800
	s_addc_u32 s1, s1, 0
	v_lshl_add_u64 v[56:57], v[2:3], 0, s[0:1]
	v_lshl_add_u64 v[58:59], v[0:1], 0, s[0:1]
	global_load_dwordx4 v[156:159], v[58:59], off offset:16
	global_load_dwordx4 v[160:163], v[56:57], off offset:16
	global_load_dwordx4 v[164:167], v[56:57], off
	global_load_dwordx4 v[168:171], v[58:59], off
	s_add_u32 s0, s0, 0x800
	s_addc_u32 s1, s1, 0
	v_lshl_add_u64 v[56:57], v[2:3], 0, s[0:1]
	v_lshl_add_u64 v[58:59], v[0:1], 0, s[0:1]
	global_load_dwordx4 v[180:183], v[58:59], off offset:16
	global_load_dwordx4 v[184:187], v[56:57], off offset:16
	global_load_dwordx4 v[188:191], v[56:57], off
	global_load_dwordx4 v[192:195], v[58:59], off
	s_add_u32 s0, s0, 0x800
	s_addc_u32 s1, s1, 0
	s_waitcnt vmcnt(30)
	v_pk_fma_f32 v[14:15], v[14:15], v[66:67], v[62:63]
	v_pk_fma_f32 v[12:13], v[12:13], v[64:65], v[60:61]
	s_waitcnt vmcnt(28)
	v_pk_fma_f32 v[10:11], v[10:11], v[70:71], v[74:75]
	v_pk_fma_f32 v[8:9], v[8:9], v[68:69], v[72:73]
	s_waitcnt vmcnt(26)
	v_pk_fma_f32 v[14:15], v[14:15], v[82:83], v[78:79]
	v_pk_fma_f32 v[12:13], v[12:13], v[80:81], v[76:77]
	s_waitcnt vmcnt(24)
	v_pk_fma_f32 v[10:11], v[10:11], v[86:87], v[90:91]
	v_pk_fma_f32 v[8:9], v[8:9], v[84:85], v[88:89]
	s_waitcnt vmcnt(22)
	v_pk_fma_f32 v[14:15], v[14:15], v[98:99], v[94:95]
	v_pk_fma_f32 v[12:13], v[12:13], v[96:97], v[92:93]
	s_waitcnt vmcnt(20)
	v_pk_fma_f32 v[10:11], v[10:11], v[102:103], v[106:107]
	v_pk_fma_f32 v[8:9], v[8:9], v[100:101], v[104:105]
	s_waitcnt vmcnt(18)
	v_pk_fma_f32 v[14:15], v[14:15], v[114:115], v[110:111]
	v_pk_fma_f32 v[12:13], v[12:13], v[112:113], v[108:109]
	s_waitcnt vmcnt(16)
	v_pk_fma_f32 v[10:11], v[10:11], v[118:119], v[122:123]
	v_pk_fma_f32 v[8:9], v[8:9], v[116:117], v[120:121]
	s_waitcnt vmcnt(14)
	v_pk_fma_f32 v[14:15], v[14:15], v[130:131], v[126:127]
	v_pk_fma_f32 v[12:13], v[12:13], v[128:129], v[124:125]
	s_waitcnt vmcnt(12)
	v_pk_fma_f32 v[10:11], v[10:11], v[134:135], v[138:139]
	v_pk_fma_f32 v[8:9], v[8:9], v[132:133], v[136:137]
	s_waitcnt vmcnt(10)
	v_pk_fma_f32 v[14:15], v[14:15], v[146:147], v[142:143]
	v_pk_fma_f32 v[12:13], v[12:13], v[144:145], v[140:141]
	s_waitcnt vmcnt(8)
	v_pk_fma_f32 v[10:11], v[10:11], v[150:151], v[154:155]
	v_pk_fma_f32 v[8:9], v[8:9], v[148:149], v[152:153]
	s_waitcnt vmcnt(6)
	v_pk_fma_f32 v[14:15], v[14:15], v[162:163], v[158:159]
	v_pk_fma_f32 v[12:13], v[12:13], v[160:161], v[156:157]
	s_waitcnt vmcnt(4)
	v_pk_fma_f32 v[10:11], v[10:11], v[166:167], v[170:171]
	v_pk_fma_f32 v[8:9], v[8:9], v[164:165], v[168:169]
	s_waitcnt vmcnt(2)
	v_pk_fma_f32 v[14:15], v[14:15], v[186:187], v[182:183]
	v_pk_fma_f32 v[12:13], v[12:13], v[184:185], v[180:181]
	s_waitcnt vmcnt(0)
	v_pk_fma_f32 v[10:11], v[10:11], v[190:191], v[194:195]
	v_pk_fma_f32 v[8:9], v[8:9], v[188:189], v[192:193]
	s_branch .Llf_chunk8

; __device__ void lru_final_item(const Params& P, int l, int item) {
;     ...
;   for (int jj = 0; jj < j; ++jj) {
;     const float* ap = P.AP + (size_t)(b * 64 + jj) * 512 + lane * 8;
;     const float* he = P.HE + (size_t)(b * 64 + jj) * 512 + lane * 8;
;     const float4 a0 = *(const float4*)ap, a1 = *(const float4*)(ap + 4);
;     const float4 h0 = *(const float4*)he, h1 = *(const float4*)(he + 4);
;     carry[0] = a0.x * carry[0] + h0.x; carry[1] = a0.y * carry[1] + h0.y; carry[2] = a0.z * carry[2] + h0.z; carry[3] = a0.w * carry[3] + h0.w;
;     carry[4] = a1.x * carry[4] + h1.x; carry[5] = a1.y * carry[5] + h1.y; carry[6] = a1.z * carry[6] + h1.z; carry[7] = a1.w * carry[7] + h1.w;
;   }
.Llf_tail:
	s_cmp_eq_u32 s4, s0
	s_cbranch_scc1 .LBB0_217
	s_sub_u32 s38, s4, s0
	s_cmp_lt_u32 s38, 0x1000
	s_cbranch_scc1 .LBB0_214
	v_lshl_add_u64 v[56:57], v[2:3], 0, s[0:1]
	v_lshl_add_u64 v[58:59], v[0:1], 0, s[0:1]
	global_load_dwordx4 v[60:63], v[58:59], off offset:16
	global_load_dwordx4 v[64:67], v[56:57], off offset:16
	global_load_dwordx4 v[68:71], v[56:57], off
	global_load_dwordx4 v[72:75], v[58:59], off
	s_add_u32 s0, s0, 0x800
	s_addc_u32 s1, s1, 0
	v_lshl_add_u64 v[56:57], v[2:3], 0, s[0:1]
	v_lshl_add_u64 v[58:59], v[0:1], 0, s[0:1]
	global_load_dwordx4 v[76:79], v[58:59], off offset:16
	global_load_dwordx4 v[80:83], v[56:57], off offset:16
	global_load_dwordx4 v[84:87], v[56:57], off
	global_load_dwordx4 v[88:91], v[58:59], off
	s_add_u32 s0, s0, 0x800
	s_addc_u32 s1, s1, 0
	s_waitcnt vmcnt(6)
	v_pk_fma_f32 v[14:15], v[14:15], v[66:67], v[62:63]
	v_pk_fma_f32 v[12:13], v[12:13], v[64:65], v[60:61]
	s_waitcnt vmcnt(4)
	v_pk_fma_f32 v[10:11], v[10:11], v[70:71], v[74:75]
	v_pk_fma_f32 v[8:9], v[8:9], v[68:69], v[72:73]
	s_waitcnt vmcnt(2)
	v_pk_fma_f32 v[14:15], v[14:15], v[82:83], v[78:79]
	v_pk_fma_f32 v[12:13], v[12:13], v[80:81], v[76:77]
	s_waitcnt vmcnt(0)
	v_pk_fma_f32 v[10:11], v[10:11], v[86:87], v[90:91]
	v_pk_fma_f32 v[8:9], v[8:9], v[84:85], v[88:89]
	s_cmp_eq_u32 s4, s0
	s_cbranch_scc1 .LBB0_217
